# best + P14 gate epilogue hand-written with packed f32 mul/add/fma (same per-element ops), all bias loads up front
# speedup vs baseline: 1.0011x; 1.0011x over previous
.LBB0_1776:
	s_and_b64 vcc, exec, s[8:9]
	s_cbranch_vccz .LBB0_1775
	v_add_u32_e32 v130, s68, v202
	v_ashrrev_i32_e32 v131, 31, v130
	v_lshl_add_u64 v[138:139], v[130:131], 2, s[56:57]
	global_load_dwordx4 v[134:137], v[138:139], off
	global_load_dwordx4 v[130:133], v[138:139], off offset:16
	global_load_dwordx4 v[142:145], v[138:139], off offset:512
	global_load_dwordx4 v[146:149], v[138:139], off offset:528
	v_mov_b32_e32 v190, 0x3fb8aa3b
	v_mov_b32_e32 v191, 0x3fb8aa3b
	v_mov_b32_e32 v192, 1.0
	v_mov_b32_e32 v193, 1.0
	s_waitcnt vmcnt(0)
	v_pk_add_f32 v[126:127], v[126:127], v[134:135]
	v_pk_add_f32 v[128:129], v[128:129], v[136:137]
	v_pk_add_f32 v[122:123], v[122:123], v[130:131]
	v_pk_add_f32 v[124:125], v[124:125], v[132:133]
	v_pk_add_f32 v[118:119], v[118:119], v[134:135]
	v_pk_add_f32 v[120:121], v[120:121], v[136:137]
	v_pk_add_f32 v[114:115], v[114:115], v[130:131]
	v_pk_add_f32 v[116:117], v[116:117], v[132:133]
	v_min_f32_e64 v150, -v122, s79
	v_min_f32_e64 v151, -v123, s79
	v_min_f32_e64 v152, -v124, s79
	v_min_f32_e64 v153, -v125, s79
	v_min_f32_e64 v154, -v126, s79
	v_min_f32_e64 v155, -v127, s79
	v_min_f32_e64 v156, -v128, s79
	v_min_f32_e64 v157, -v129, s79
	v_min_f32_e64 v166, -v114, s79
	v_min_f32_e64 v167, -v115, s79
	v_min_f32_e64 v168, -v116, s79
	v_min_f32_e64 v169, -v117, s79
	v_min_f32_e64 v170, -v118, s79
	v_min_f32_e64 v171, -v119, s79
	v_min_f32_e64 v172, -v120, s79
	v_min_f32_e64 v173, -v121, s79
	v_pk_mul_f32 v[150:151], v[150:151], v[190:191]
	v_pk_mul_f32 v[152:153], v[152:153], v[190:191]
	v_pk_mul_f32 v[154:155], v[154:155], v[190:191]
	v_pk_mul_f32 v[156:157], v[156:157], v[190:191]
	v_pk_mul_f32 v[166:167], v[166:167], v[190:191]
	v_pk_mul_f32 v[168:169], v[168:169], v[190:191]
	v_pk_mul_f32 v[170:171], v[170:171], v[190:191]
	v_pk_mul_f32 v[172:173], v[172:173], v[190:191]
	v_exp_f32_e32 v150, v150
	v_exp_f32_e32 v151, v151
	v_exp_f32_e32 v152, v152
	v_exp_f32_e32 v153, v153
	v_exp_f32_e32 v154, v154
	v_exp_f32_e32 v155, v155
	v_exp_f32_e32 v156, v156
	v_exp_f32_e32 v157, v157
	v_exp_f32_e32 v166, v166
	v_exp_f32_e32 v167, v167
	v_exp_f32_e32 v168, v168
	v_exp_f32_e32 v169, v169
	v_exp_f32_e32 v170, v170
	v_exp_f32_e32 v171, v171
	v_exp_f32_e32 v172, v172
	v_exp_f32_e32 v173, v173
	v_add_co_u32_e32 v184, vcc, s70, v200
	s_nop 1
	v_addc_co_u32_e32 v185, vcc, 0, v201, vcc
	v_pk_add_f32 v[150:151], v[150:151], v[192:193]
	v_pk_add_f32 v[152:153], v[152:153], v[192:193]
	v_pk_add_f32 v[154:155], v[154:155], v[192:193]
	v_pk_add_f32 v[156:157], v[156:157], v[192:193]
	v_pk_add_f32 v[166:167], v[166:167], v[192:193]
	v_pk_add_f32 v[168:169], v[168:169], v[192:193]
	v_pk_add_f32 v[170:171], v[170:171], v[192:193]
	v_pk_add_f32 v[172:173], v[172:173], v[192:193]
	v_rcp_f32_e32 v158, v150
	v_rcp_f32_e32 v159, v151
	v_rcp_f32_e32 v160, v152
	v_rcp_f32_e32 v161, v153
	v_rcp_f32_e32 v162, v154
	v_rcp_f32_e32 v163, v155
	v_rcp_f32_e32 v164, v156
	v_rcp_f32_e32 v165, v157
	v_rcp_f32_e32 v174, v166
	v_rcp_f32_e32 v175, v167
	v_rcp_f32_e32 v176, v168
	v_rcp_f32_e32 v177, v169
	v_rcp_f32_e32 v178, v170
	v_rcp_f32_e32 v179, v171
	v_rcp_f32_e32 v180, v172
	v_rcp_f32_e32 v181, v173
	s_nop 0
	v_pk_fma_f32 v[150:151], v[150:151], v[158:159], v[192:193] neg_lo:[1,0,0] neg_hi:[1,0,0]
	v_pk_fma_f32 v[152:153], v[152:153], v[160:161], v[192:193] neg_lo:[1,0,0] neg_hi:[1,0,0]
	v_pk_fma_f32 v[154:155], v[154:155], v[162:163], v[192:193] neg_lo:[1,0,0] neg_hi:[1,0,0]
	v_pk_fma_f32 v[156:157], v[156:157], v[164:165], v[192:193] neg_lo:[1,0,0] neg_hi:[1,0,0]
	v_pk_fma_f32 v[166:167], v[166:167], v[174:175], v[192:193] neg_lo:[1,0,0] neg_hi:[1,0,0]
	v_pk_fma_f32 v[168:169], v[168:169], v[176:177], v[192:193] neg_lo:[1,0,0] neg_hi:[1,0,0]
	v_pk_fma_f32 v[170:171], v[170:171], v[178:179], v[192:193] neg_lo:[1,0,0] neg_hi:[1,0,0]
	v_pk_fma_f32 v[172:173], v[172:173], v[180:181], v[192:193] neg_lo:[1,0,0] neg_hi:[1,0,0]
	v_pk_fma_f32 v[158:159], v[150:151], v[158:159], v[158:159]
	v_pk_fma_f32 v[160:161], v[152:153], v[160:161], v[160:161]
	v_pk_fma_f32 v[162:163], v[154:155], v[162:163], v[162:163]
	v_pk_fma_f32 v[164:165], v[156:157], v[164:165], v[164:165]
	v_pk_fma_f32 v[174:175], v[166:167], v[174:175], v[174:175]
	v_pk_fma_f32 v[176:177], v[168:169], v[176:177], v[176:177]
	v_pk_fma_f32 v[178:179], v[170:171], v[178:179], v[178:179]
	v_pk_fma_f32 v[180:181], v[172:173], v[180:181], v[180:181]
	v_cvt_pk_bf16_f32 v150, v162, v163
	v_cvt_pk_bf16_f32 v151, v164, v165
	v_cvt_pk_bf16_f32 v152, v158, v159
	v_cvt_pk_bf16_f32 v153, v160, v161
	v_cvt_pk_bf16_f32 v166, v178, v179
	v_cvt_pk_bf16_f32 v167, v180, v181
	v_cvt_pk_bf16_f32 v168, v174, v175
	v_cvt_pk_bf16_f32 v169, v176, v177
	global_store_dwordx4 v[200:201], v[150:153], off
	global_store_dwordx4 v[184:185], v[166:169], off
	v_pk_add_f32 v[110:111], v[110:111], v[134:135]
	v_pk_add_f32 v[112:113], v[112:113], v[136:137]
	v_pk_add_f32 v[106:107], v[106:107], v[130:131]
	v_pk_add_f32 v[108:109], v[108:109], v[132:133]
	v_pk_add_f32 v[102:103], v[102:103], v[134:135]
	v_pk_add_f32 v[104:105], v[104:105], v[136:137]
	v_pk_add_f32 v[98:99], v[98:99], v[130:131]
	v_pk_add_f32 v[100:101], v[100:101], v[132:133]
	v_min_f32_e64 v150, -v106, s79
	v_min_f32_e64 v151, -v107, s79
	v_min_f32_e64 v152, -v108, s79
	v_min_f32_e64 v153, -v109, s79
	v_min_f32_e64 v154, -v110, s79
	v_min_f32_e64 v155, -v111, s79
	v_min_f32_e64 v156, -v112, s79
	v_min_f32_e64 v157, -v113, s79
	v_min_f32_e64 v166, -v98, s79
	v_min_f32_e64 v167, -v99, s79
	v_min_f32_e64 v168, -v100, s79
	v_min_f32_e64 v169, -v101, s79
	v_min_f32_e64 v170, -v102, s79
	v_min_f32_e64 v171, -v103, s79
	v_min_f32_e64 v172, -v104, s79
	v_min_f32_e64 v173, -v105, s79
	v_pk_mul_f32 v[150:151], v[150:151], v[190:191]
	v_pk_mul_f32 v[152:153], v[152:153], v[190:191]
	v_pk_mul_f32 v[154:155], v[154:155], v[190:191]
	v_pk_mul_f32 v[156:157], v[156:157], v[190:191]
	v_pk_mul_f32 v[166:167], v[166:167], v[190:191]
	v_pk_mul_f32 v[168:169], v[168:169], v[190:191]
	v_pk_mul_f32 v[170:171], v[170:171], v[190:191]
	v_pk_mul_f32 v[172:173], v[172:173], v[190:191]
	v_exp_f32_e32 v150, v150
	v_exp_f32_e32 v151, v151
	v_exp_f32_e32 v152, v152
	v_exp_f32_e32 v153, v153
	v_exp_f32_e32 v154, v154
	v_exp_f32_e32 v155, v155
	v_exp_f32_e32 v156, v156
	v_exp_f32_e32 v157, v157
	v_exp_f32_e32 v166, v166
	v_exp_f32_e32 v167, v167
	v_exp_f32_e32 v168, v168
	v_exp_f32_e32 v169, v169
	v_exp_f32_e32 v170, v170
	v_exp_f32_e32 v171, v171
	v_exp_f32_e32 v172, v172
	v_exp_f32_e32 v173, v173
	v_add_co_u32_e32 v182, vcc, 0x10000, v200
	s_nop 1
	v_addc_co_u32_e32 v183, vcc, 0, v201, vcc
	v_add_co_u32_e32 v184, vcc, s69, v200
	s_nop 1
	v_addc_co_u32_e32 v185, vcc, 0, v201, vcc
	v_pk_add_f32 v[150:151], v[150:151], v[192:193]
	v_pk_add_f32 v[152:153], v[152:153], v[192:193]
	v_pk_add_f32 v[154:155], v[154:155], v[192:193]
	v_pk_add_f32 v[156:157], v[156:157], v[192:193]
	v_pk_add_f32 v[166:167], v[166:167], v[192:193]
	v_pk_add_f32 v[168:169], v[168:169], v[192:193]
	v_pk_add_f32 v[170:171], v[170:171], v[192:193]
	v_pk_add_f32 v[172:173], v[172:173], v[192:193]
	v_rcp_f32_e32 v158, v150
	v_rcp_f32_e32 v159, v151
	v_rcp_f32_e32 v160, v152
	v_rcp_f32_e32 v161, v153
	v_rcp_f32_e32 v162, v154
	v_rcp_f32_e32 v163, v155
	v_rcp_f32_e32 v164, v156
	v_rcp_f32_e32 v165, v157
	v_rcp_f32_e32 v174, v166
	v_rcp_f32_e32 v175, v167
	v_rcp_f32_e32 v176, v168
	v_rcp_f32_e32 v177, v169
	v_rcp_f32_e32 v178, v170
	v_rcp_f32_e32 v179, v171
	v_rcp_f32_e32 v180, v172
	v_rcp_f32_e32 v181, v173
	s_nop 0
	v_pk_fma_f32 v[150:151], v[150:151], v[158:159], v[192:193] neg_lo:[1,0,0] neg_hi:[1,0,0]
	v_pk_fma_f32 v[152:153], v[152:153], v[160:161], v[192:193] neg_lo:[1,0,0] neg_hi:[1,0,0]
	v_pk_fma_f32 v[154:155], v[154:155], v[162:163], v[192:193] neg_lo:[1,0,0] neg_hi:[1,0,0]
	v_pk_fma_f32 v[156:157], v[156:157], v[164:165], v[192:193] neg_lo:[1,0,0] neg_hi:[1,0,0]
	v_pk_fma_f32 v[166:167], v[166:167], v[174:175], v[192:193] neg_lo:[1,0,0] neg_hi:[1,0,0]
	v_pk_fma_f32 v[168:169], v[168:169], v[176:177], v[192:193] neg_lo:[1,0,0] neg_hi:[1,0,0]
	v_pk_fma_f32 v[170:171], v[170:171], v[178:179], v[192:193] neg_lo:[1,0,0] neg_hi:[1,0,0]
	v_pk_fma_f32 v[172:173], v[172:173], v[180:181], v[192:193] neg_lo:[1,0,0] neg_hi:[1,0,0]
	v_pk_fma_f32 v[158:159], v[150:151], v[158:159], v[158:159]
	v_pk_fma_f32 v[160:161], v[152:153], v[160:161], v[160:161]
	v_pk_fma_f32 v[162:163], v[154:155], v[162:163], v[162:163]
	v_pk_fma_f32 v[164:165], v[156:157], v[164:165], v[164:165]
	v_pk_fma_f32 v[174:175], v[166:167], v[174:175], v[174:175]
	v_pk_fma_f32 v[176:177], v[168:169], v[176:177], v[176:177]
	v_pk_fma_f32 v[178:179], v[170:171], v[178:179], v[178:179]
	v_pk_fma_f32 v[180:181], v[172:173], v[180:181], v[180:181]
	v_cvt_pk_bf16_f32 v150, v162, v163
	v_cvt_pk_bf16_f32 v151, v164, v165
	v_cvt_pk_bf16_f32 v152, v158, v159
	v_cvt_pk_bf16_f32 v153, v160, v161
	v_cvt_pk_bf16_f32 v166, v178, v179
	v_cvt_pk_bf16_f32 v167, v180, v181
	v_cvt_pk_bf16_f32 v168, v174, v175
	v_cvt_pk_bf16_f32 v169, v176, v177
	global_store_dwordx4 v[182:183], v[150:153], off
	global_store_dwordx4 v[184:185], v[166:169], off
	v_pk_add_f32 v[94:95], v[94:95], v[134:135]
	v_pk_add_f32 v[96:97], v[96:97], v[136:137]
	v_pk_add_f32 v[90:91], v[90:91], v[130:131]
	v_pk_add_f32 v[92:93], v[92:93], v[132:133]
	v_pk_add_f32 v[86:87], v[86:87], v[134:135]
	v_pk_add_f32 v[88:89], v[88:89], v[136:137]
	v_pk_add_f32 v[82:83], v[82:83], v[130:131]
	v_pk_add_f32 v[84:85], v[84:85], v[132:133]
	v_min_f32_e64 v150, -v90, s79
	v_min_f32_e64 v151, -v91, s79
	v_min_f32_e64 v152, -v92, s79
	v_min_f32_e64 v153, -v93, s79
	v_min_f32_e64 v154, -v94, s79
	v_min_f32_e64 v155, -v95, s79
	v_min_f32_e64 v156, -v96, s79
	v_min_f32_e64 v157, -v97, s79
	v_min_f32_e64 v166, -v82, s79
	v_min_f32_e64 v167, -v83, s79
	v_min_f32_e64 v168, -v84, s79
	v_min_f32_e64 v169, -v85, s79
	v_min_f32_e64 v170, -v86, s79
	v_min_f32_e64 v171, -v87, s79
	v_min_f32_e64 v172, -v88, s79
	v_min_f32_e64 v173, -v89, s79
	v_pk_mul_f32 v[150:151], v[150:151], v[190:191]
	v_pk_mul_f32 v[152:153], v[152:153], v[190:191]
	v_pk_mul_f32 v[154:155], v[154:155], v[190:191]
	v_pk_mul_f32 v[156:157], v[156:157], v[190:191]
	v_pk_mul_f32 v[166:167], v[166:167], v[190:191]
	v_pk_mul_f32 v[168:169], v[168:169], v[190:191]
	v_pk_mul_f32 v[170:171], v[170:171], v[190:191]
	v_pk_mul_f32 v[172:173], v[172:173], v[190:191]
	v_exp_f32_e32 v150, v150
	v_exp_f32_e32 v151, v151
	v_exp_f32_e32 v152, v152
	v_exp_f32_e32 v153, v153
	v_exp_f32_e32 v154, v154
	v_exp_f32_e32 v155, v155
	v_exp_f32_e32 v156, v156
	v_exp_f32_e32 v157, v157
	v_exp_f32_e32 v166, v166
	v_exp_f32_e32 v167, v167
	v_exp_f32_e32 v168, v168
	v_exp_f32_e32 v169, v169
	v_exp_f32_e32 v170, v170
	v_exp_f32_e32 v171, v171
	v_exp_f32_e32 v172, v172
	v_exp_f32_e32 v173, v173
	v_add_co_u32_e32 v182, vcc, s75, v200
	s_nop 1
	v_addc_co_u32_e32 v183, vcc, 0, v201, vcc
	v_add_co_u32_e32 v184, vcc, s76, v200
	s_nop 1
	v_addc_co_u32_e32 v185, vcc, 0, v201, vcc
	v_pk_add_f32 v[150:151], v[150:151], v[192:193]
	v_pk_add_f32 v[152:153], v[152:153], v[192:193]
	v_pk_add_f32 v[154:155], v[154:155], v[192:193]
	v_pk_add_f32 v[156:157], v[156:157], v[192:193]
	v_pk_add_f32 v[166:167], v[166:167], v[192:193]
	v_pk_add_f32 v[168:169], v[168:169], v[192:193]
	v_pk_add_f32 v[170:171], v[170:171], v[192:193]
	v_pk_add_f32 v[172:173], v[172:173], v[192:193]
	v_rcp_f32_e32 v158, v150
	v_rcp_f32_e32 v159, v151
	v_rcp_f32_e32 v160, v152
	v_rcp_f32_e32 v161, v153
	v_rcp_f32_e32 v162, v154
	v_rcp_f32_e32 v163, v155
	v_rcp_f32_e32 v164, v156
	v_rcp_f32_e32 v165, v157
	v_rcp_f32_e32 v174, v166
	v_rcp_f32_e32 v175, v167
	v_rcp_f32_e32 v176, v168
	v_rcp_f32_e32 v177, v169
	v_rcp_f32_e32 v178, v170
	v_rcp_f32_e32 v179, v171
	v_rcp_f32_e32 v180, v172
	v_rcp_f32_e32 v181, v173
	s_nop 0
	v_pk_fma_f32 v[150:151], v[150:151], v[158:159], v[192:193] neg_lo:[1,0,0] neg_hi:[1,0,0]
	v_pk_fma_f32 v[152:153], v[152:153], v[160:161], v[192:193] neg_lo:[1,0,0] neg_hi:[1,0,0]
	v_pk_fma_f32 v[154:155], v[154:155], v[162:163], v[192:193] neg_lo:[1,0,0] neg_hi:[1,0,0]
	v_pk_fma_f32 v[156:157], v[156:157], v[164:165], v[192:193] neg_lo:[1,0,0] neg_hi:[1,0,0]
	v_pk_fma_f32 v[166:167], v[166:167], v[174:175], v[192:193] neg_lo:[1,0,0] neg_hi:[1,0,0]
	v_pk_fma_f32 v[168:169], v[168:169], v[176:177], v[192:193] neg_lo:[1,0,0] neg_hi:[1,0,0]
	v_pk_fma_f32 v[170:171], v[170:171], v[178:179], v[192:193] neg_lo:[1,0,0] neg_hi:[1,0,0]
	v_pk_fma_f32 v[172:173], v[172:173], v[180:181], v[192:193] neg_lo:[1,0,0] neg_hi:[1,0,0]
	v_pk_fma_f32 v[158:159], v[150:151], v[158:159], v[158:159]
	v_pk_fma_f32 v[160:161], v[152:153], v[160:161], v[160:161]
	v_pk_fma_f32 v[162:163], v[154:155], v[162:163], v[162:163]
	v_pk_fma_f32 v[164:165], v[156:157], v[164:165], v[164:165]
	v_pk_fma_f32 v[174:175], v[166:167], v[174:175], v[174:175]
	v_pk_fma_f32 v[176:177], v[168:169], v[176:177], v[176:177]
	v_pk_fma_f32 v[178:179], v[170:171], v[178:179], v[178:179]
	v_pk_fma_f32 v[180:181], v[172:173], v[180:181], v[180:181]
	v_cvt_pk_bf16_f32 v150, v162, v163
	v_cvt_pk_bf16_f32 v151, v164, v165
	v_cvt_pk_bf16_f32 v152, v158, v159
	v_cvt_pk_bf16_f32 v153, v160, v161
	v_cvt_pk_bf16_f32 v166, v178, v179
	v_cvt_pk_bf16_f32 v167, v180, v181
	v_cvt_pk_bf16_f32 v168, v174, v175
	v_cvt_pk_bf16_f32 v169, v176, v177
	global_store_dwordx4 v[182:183], v[150:153], off
	global_store_dwordx4 v[184:185], v[166:169], off
	v_pk_add_f32 v[78:79], v[78:79], v[134:135]
	v_pk_add_f32 v[80:81], v[80:81], v[136:137]
	v_pk_add_f32 v[74:75], v[74:75], v[130:131]
	v_pk_add_f32 v[76:77], v[76:77], v[132:133]
	v_pk_add_f32 v[70:71], v[70:71], v[134:135]
	v_pk_add_f32 v[72:73], v[72:73], v[136:137]
	v_pk_add_f32 v[66:67], v[66:67], v[130:131]
	v_pk_add_f32 v[68:69], v[68:69], v[132:133]
	v_min_f32_e64 v150, -v74, s79
	v_min_f32_e64 v151, -v75, s79
	v_min_f32_e64 v152, -v76, s79
	v_min_f32_e64 v153, -v77, s79
	v_min_f32_e64 v154, -v78, s79
	v_min_f32_e64 v155, -v79, s79
	v_min_f32_e64 v156, -v80, s79
	v_min_f32_e64 v157, -v81, s79
	v_min_f32_e64 v166, -v66, s79
	v_min_f32_e64 v167, -v67, s79
	v_min_f32_e64 v168, -v68, s79
	v_min_f32_e64 v169, -v69, s79
	v_min_f32_e64 v170, -v70, s79
	v_min_f32_e64 v171, -v71, s79
	v_min_f32_e64 v172, -v72, s79
	v_min_f32_e64 v173, -v73, s79
	v_pk_mul_f32 v[150:151], v[150:151], v[190:191]
	v_pk_mul_f32 v[152:153], v[152:153], v[190:191]
	v_pk_mul_f32 v[154:155], v[154:155], v[190:191]
	v_pk_mul_f32 v[156:157], v[156:157], v[190:191]
	v_pk_mul_f32 v[166:167], v[166:167], v[190:191]
	v_pk_mul_f32 v[168:169], v[168:169], v[190:191]
	v_pk_mul_f32 v[170:171], v[170:171], v[190:191]
	v_pk_mul_f32 v[172:173], v[172:173], v[190:191]
	v_exp_f32_e32 v150, v150
	v_exp_f32_e32 v151, v151
	v_exp_f32_e32 v152, v152
	v_exp_f32_e32 v153, v153
	v_exp_f32_e32 v154, v154
	v_exp_f32_e32 v155, v155
	v_exp_f32_e32 v156, v156
	v_exp_f32_e32 v157, v157
	v_exp_f32_e32 v166, v166
	v_exp_f32_e32 v167, v167
	v_exp_f32_e32 v168, v168
	v_exp_f32_e32 v169, v169
	v_exp_f32_e32 v170, v170
	v_exp_f32_e32 v171, v171
	v_exp_f32_e32 v172, v172
	v_exp_f32_e32 v173, v173
	v_add_co_u32_e32 v182, vcc, s77, v200
	s_nop 1
	v_addc_co_u32_e32 v183, vcc, 0, v201, vcc
	v_add_co_u32_e32 v184, vcc, s78, v200
	s_nop 1
	v_addc_co_u32_e32 v185, vcc, 0, v201, vcc
	v_pk_add_f32 v[150:151], v[150:151], v[192:193]
	v_pk_add_f32 v[152:153], v[152:153], v[192:193]
	v_pk_add_f32 v[154:155], v[154:155], v[192:193]
	v_pk_add_f32 v[156:157], v[156:157], v[192:193]
	v_pk_add_f32 v[166:167], v[166:167], v[192:193]
	v_pk_add_f32 v[168:169], v[168:169], v[192:193]
	v_pk_add_f32 v[170:171], v[170:171], v[192:193]
	v_pk_add_f32 v[172:173], v[172:173], v[192:193]
	v_rcp_f32_e32 v158, v150
	v_rcp_f32_e32 v159, v151
	v_rcp_f32_e32 v160, v152
	v_rcp_f32_e32 v161, v153
	v_rcp_f32_e32 v162, v154
	v_rcp_f32_e32 v163, v155
	v_rcp_f32_e32 v164, v156
	v_rcp_f32_e32 v165, v157
	v_rcp_f32_e32 v174, v166
	v_rcp_f32_e32 v175, v167
	v_rcp_f32_e32 v176, v168
	v_rcp_f32_e32 v177, v169
	v_rcp_f32_e32 v178, v170
	v_rcp_f32_e32 v179, v171
	v_rcp_f32_e32 v180, v172
	v_rcp_f32_e32 v181, v173
	s_nop 0
	v_pk_fma_f32 v[150:151], v[150:151], v[158:159], v[192:193] neg_lo:[1,0,0] neg_hi:[1,0,0]
	v_pk_fma_f32 v[152:153], v[152:153], v[160:161], v[192:193] neg_lo:[1,0,0] neg_hi:[1,0,0]
	v_pk_fma_f32 v[154:155], v[154:155], v[162:163], v[192:193] neg_lo:[1,0,0] neg_hi:[1,0,0]
	v_pk_fma_f32 v[156:157], v[156:157], v[164:165], v[192:193] neg_lo:[1,0,0] neg_hi:[1,0,0]
	v_pk_fma_f32 v[166:167], v[166:167], v[174:175], v[192:193] neg_lo:[1,0,0] neg_hi:[1,0,0]
	v_pk_fma_f32 v[168:169], v[168:169], v[176:177], v[192:193] neg_lo:[1,0,0] neg_hi:[1,0,0]
	v_pk_fma_f32 v[170:171], v[170:171], v[178:179], v[192:193] neg_lo:[1,0,0] neg_hi:[1,0,0]
	v_pk_fma_f32 v[172:173], v[172:173], v[180:181], v[192:193] neg_lo:[1,0,0] neg_hi:[1,0,0]
	v_pk_fma_f32 v[158:159], v[150:151], v[158:159], v[158:159]
	v_pk_fma_f32 v[160:161], v[152:153], v[160:161], v[160:161]
	v_pk_fma_f32 v[162:163], v[154:155], v[162:163], v[162:163]
	v_pk_fma_f32 v[164:165], v[156:157], v[164:165], v[164:165]
	v_pk_fma_f32 v[174:175], v[166:167], v[174:175], v[174:175]
	v_pk_fma_f32 v[176:177], v[168:169], v[176:177], v[176:177]
	v_pk_fma_f32 v[178:179], v[170:171], v[178:179], v[178:179]
	v_pk_fma_f32 v[180:181], v[172:173], v[180:181], v[180:181]
	v_cvt_pk_bf16_f32 v150, v162, v163
	v_cvt_pk_bf16_f32 v151, v164, v165
	v_cvt_pk_bf16_f32 v152, v158, v159
	v_cvt_pk_bf16_f32 v153, v160, v161
	v_cvt_pk_bf16_f32 v166, v178, v179
	v_cvt_pk_bf16_f32 v167, v180, v181
	v_cvt_pk_bf16_f32 v168, v174, v175
	v_cvt_pk_bf16_f32 v169, v176, v177
	global_store_dwordx4 v[182:183], v[150:153], off
	global_store_dwordx4 v[184:185], v[166:169], off
	v_pk_add_f32 v[62:63], v[62:63], v[142:143]
	v_pk_add_f32 v[64:65], v[64:65], v[144:145]
	v_pk_add_f32 v[58:59], v[58:59], v[146:147]
	v_pk_add_f32 v[60:61], v[60:61], v[148:149]
	v_pk_add_f32 v[54:55], v[54:55], v[142:143]
	v_pk_add_f32 v[56:57], v[56:57], v[144:145]
	v_pk_add_f32 v[50:51], v[50:51], v[146:147]
	v_pk_add_f32 v[52:53], v[52:53], v[148:149]
	v_min_f32_e64 v150, -v58, s79
	v_min_f32_e64 v151, -v59, s79
	v_min_f32_e64 v152, -v60, s79
	v_min_f32_e64 v153, -v61, s79
	v_min_f32_e64 v154, -v62, s79
	v_min_f32_e64 v155, -v63, s79
	v_min_f32_e64 v156, -v64, s79
	v_min_f32_e64 v157, -v65, s79
	v_min_f32_e64 v166, -v50, s79
	v_min_f32_e64 v167, -v51, s79
	v_min_f32_e64 v168, -v52, s79
	v_min_f32_e64 v169, -v53, s79
	v_min_f32_e64 v170, -v54, s79
	v_min_f32_e64 v171, -v55, s79
	v_min_f32_e64 v172, -v56, s79
	v_min_f32_e64 v173, -v57, s79
	v_pk_mul_f32 v[150:151], v[150:151], v[190:191]
	v_pk_mul_f32 v[152:153], v[152:153], v[190:191]
	v_pk_mul_f32 v[154:155], v[154:155], v[190:191]
	v_pk_mul_f32 v[156:157], v[156:157], v[190:191]
	v_pk_mul_f32 v[166:167], v[166:167], v[190:191]
	v_pk_mul_f32 v[168:169], v[168:169], v[190:191]
	v_pk_mul_f32 v[170:171], v[170:171], v[190:191]
	v_pk_mul_f32 v[172:173], v[172:173], v[190:191]
	v_exp_f32_e32 v150, v150
	v_exp_f32_e32 v151, v151
	v_exp_f32_e32 v152, v152
	v_exp_f32_e32 v153, v153
	v_exp_f32_e32 v154, v154
	v_exp_f32_e32 v155, v155
	v_exp_f32_e32 v156, v156
	v_exp_f32_e32 v157, v157
	v_exp_f32_e32 v166, v166
	v_exp_f32_e32 v167, v167
	v_exp_f32_e32 v168, v168
	v_exp_f32_e32 v169, v169
	v_exp_f32_e32 v170, v170
	v_exp_f32_e32 v171, v171
	v_exp_f32_e32 v172, v172
	v_exp_f32_e32 v173, v173
	v_add_co_u32_e32 v184, vcc, s70, v200
	s_nop 1
	v_addc_co_u32_e32 v185, vcc, 0, v201, vcc
	v_pk_add_f32 v[150:151], v[150:151], v[192:193]
	v_pk_add_f32 v[152:153], v[152:153], v[192:193]
	v_pk_add_f32 v[154:155], v[154:155], v[192:193]
	v_pk_add_f32 v[156:157], v[156:157], v[192:193]
	v_pk_add_f32 v[166:167], v[166:167], v[192:193]
	v_pk_add_f32 v[168:169], v[168:169], v[192:193]
	v_pk_add_f32 v[170:171], v[170:171], v[192:193]
	v_pk_add_f32 v[172:173], v[172:173], v[192:193]
	v_rcp_f32_e32 v158, v150
	v_rcp_f32_e32 v159, v151
	v_rcp_f32_e32 v160, v152
	v_rcp_f32_e32 v161, v153
	v_rcp_f32_e32 v162, v154
	v_rcp_f32_e32 v163, v155
	v_rcp_f32_e32 v164, v156
	v_rcp_f32_e32 v165, v157
	v_rcp_f32_e32 v174, v166
	v_rcp_f32_e32 v175, v167
	v_rcp_f32_e32 v176, v168
	v_rcp_f32_e32 v177, v169
	v_rcp_f32_e32 v178, v170
	v_rcp_f32_e32 v179, v171
	v_rcp_f32_e32 v180, v172
	v_rcp_f32_e32 v181, v173
	s_nop 0
	v_pk_fma_f32 v[150:151], v[150:151], v[158:159], v[192:193] neg_lo:[1,0,0] neg_hi:[1,0,0]
	v_pk_fma_f32 v[152:153], v[152:153], v[160:161], v[192:193] neg_lo:[1,0,0] neg_hi:[1,0,0]
	v_pk_fma_f32 v[154:155], v[154:155], v[162:163], v[192:193] neg_lo:[1,0,0] neg_hi:[1,0,0]
	v_pk_fma_f32 v[156:157], v[156:157], v[164:165], v[192:193] neg_lo:[1,0,0] neg_hi:[1,0,0]
	v_pk_fma_f32 v[166:167], v[166:167], v[174:175], v[192:193] neg_lo:[1,0,0] neg_hi:[1,0,0]
	v_pk_fma_f32 v[168:169], v[168:169], v[176:177], v[192:193] neg_lo:[1,0,0] neg_hi:[1,0,0]
	v_pk_fma_f32 v[170:171], v[170:171], v[178:179], v[192:193] neg_lo:[1,0,0] neg_hi:[1,0,0]
	v_pk_fma_f32 v[172:173], v[172:173], v[180:181], v[192:193] neg_lo:[1,0,0] neg_hi:[1,0,0]
	v_pk_fma_f32 v[158:159], v[150:151], v[158:159], v[158:159]
	v_pk_fma_f32 v[160:161], v[152:153], v[160:161], v[160:161]
	v_pk_fma_f32 v[162:163], v[154:155], v[162:163], v[162:163]
	v_pk_fma_f32 v[164:165], v[156:157], v[164:165], v[164:165]
	v_pk_fma_f32 v[174:175], v[166:167], v[174:175], v[174:175]
	v_pk_fma_f32 v[176:177], v[168:169], v[176:177], v[176:177]
	v_pk_fma_f32 v[178:179], v[170:171], v[178:179], v[178:179]
	v_pk_fma_f32 v[180:181], v[172:173], v[180:181], v[180:181]
	v_cvt_pk_bf16_f32 v150, v162, v163
	v_cvt_pk_bf16_f32 v151, v164, v165
	v_cvt_pk_bf16_f32 v152, v158, v159
	v_cvt_pk_bf16_f32 v153, v160, v161
	v_cvt_pk_bf16_f32 v166, v178, v179
	v_cvt_pk_bf16_f32 v167, v180, v181
	v_cvt_pk_bf16_f32 v168, v174, v175
	v_cvt_pk_bf16_f32 v169, v176, v177
	global_store_dwordx4 v[200:201], v[150:153], off offset:256
	global_store_dwordx4 v[184:185], v[166:169], off offset:256
	v_pk_add_f32 v[46:47], v[46:47], v[142:143]
	v_pk_add_f32 v[48:49], v[48:49], v[144:145]
	v_pk_add_f32 v[42:43], v[42:43], v[146:147]
	v_pk_add_f32 v[44:45], v[44:45], v[148:149]
	v_pk_add_f32 v[38:39], v[38:39], v[142:143]
	v_pk_add_f32 v[40:41], v[40:41], v[144:145]
	v_pk_add_f32 v[34:35], v[34:35], v[146:147]
	v_pk_add_f32 v[36:37], v[36:37], v[148:149]
	v_min_f32_e64 v150, -v42, s79
	v_min_f32_e64 v151, -v43, s79
	v_min_f32_e64 v152, -v44, s79
	v_min_f32_e64 v153, -v45, s79
	v_min_f32_e64 v154, -v46, s79
	v_min_f32_e64 v155, -v47, s79
	v_min_f32_e64 v156, -v48, s79
	v_min_f32_e64 v157, -v49, s79
	v_min_f32_e64 v166, -v34, s79
	v_min_f32_e64 v167, -v35, s79
	v_min_f32_e64 v168, -v36, s79
	v_min_f32_e64 v169, -v37, s79
	v_min_f32_e64 v170, -v38, s79
	v_min_f32_e64 v171, -v39, s79
	v_min_f32_e64 v172, -v40, s79
	v_min_f32_e64 v173, -v41, s79
	v_pk_mul_f32 v[150:151], v[150:151], v[190:191]
	v_pk_mul_f32 v[152:153], v[152:153], v[190:191]
	v_pk_mul_f32 v[154:155], v[154:155], v[190:191]
	v_pk_mul_f32 v[156:157], v[156:157], v[190:191]
	v_pk_mul_f32 v[166:167], v[166:167], v[190:191]
	v_pk_mul_f32 v[168:169], v[168:169], v[190:191]
	v_pk_mul_f32 v[170:171], v[170:171], v[190:191]
	v_pk_mul_f32 v[172:173], v[172:173], v[190:191]
	v_exp_f32_e32 v150, v150
	v_exp_f32_e32 v151, v151
	v_exp_f32_e32 v152, v152
	v_exp_f32_e32 v153, v153
	v_exp_f32_e32 v154, v154
	v_exp_f32_e32 v155, v155
	v_exp_f32_e32 v156, v156
	v_exp_f32_e32 v157, v157
	v_exp_f32_e32 v166, v166
	v_exp_f32_e32 v167, v167
	v_exp_f32_e32 v168, v168
	v_exp_f32_e32 v169, v169
	v_exp_f32_e32 v170, v170
	v_exp_f32_e32 v171, v171
	v_exp_f32_e32 v172, v172
	v_exp_f32_e32 v173, v173
	v_add_co_u32_e32 v182, vcc, 0x10000, v200
	s_nop 1
	v_addc_co_u32_e32 v183, vcc, 0, v201, vcc
	v_add_co_u32_e32 v184, vcc, s69, v200
	s_nop 1
	v_addc_co_u32_e32 v185, vcc, 0, v201, vcc
	v_pk_add_f32 v[150:151], v[150:151], v[192:193]
	v_pk_add_f32 v[152:153], v[152:153], v[192:193]
	v_pk_add_f32 v[154:155], v[154:155], v[192:193]
	v_pk_add_f32 v[156:157], v[156:157], v[192:193]
	v_pk_add_f32 v[166:167], v[166:167], v[192:193]
	v_pk_add_f32 v[168:169], v[168:169], v[192:193]
	v_pk_add_f32 v[170:171], v[170:171], v[192:193]
	v_pk_add_f32 v[172:173], v[172:173], v[192:193]
	v_rcp_f32_e32 v158, v150
	v_rcp_f32_e32 v159, v151
	v_rcp_f32_e32 v160, v152
	v_rcp_f32_e32 v161, v153
	v_rcp_f32_e32 v162, v154
	v_rcp_f32_e32 v163, v155
	v_rcp_f32_e32 v164, v156
	v_rcp_f32_e32 v165, v157
	v_rcp_f32_e32 v174, v166
	v_rcp_f32_e32 v175, v167
	v_rcp_f32_e32 v176, v168
	v_rcp_f32_e32 v177, v169
	v_rcp_f32_e32 v178, v170
	v_rcp_f32_e32 v179, v171
	v_rcp_f32_e32 v180, v172
	v_rcp_f32_e32 v181, v173
	s_nop 0
	v_pk_fma_f32 v[150:151], v[150:151], v[158:159], v[192:193] neg_lo:[1,0,0] neg_hi:[1,0,0]
	v_pk_fma_f32 v[152:153], v[152:153], v[160:161], v[192:193] neg_lo:[1,0,0] neg_hi:[1,0,0]
	v_pk_fma_f32 v[154:155], v[154:155], v[162:163], v[192:193] neg_lo:[1,0,0] neg_hi:[1,0,0]
	v_pk_fma_f32 v[156:157], v[156:157], v[164:165], v[192:193] neg_lo:[1,0,0] neg_hi:[1,0,0]
	v_pk_fma_f32 v[166:167], v[166:167], v[174:175], v[192:193] neg_lo:[1,0,0] neg_hi:[1,0,0]
	v_pk_fma_f32 v[168:169], v[168:169], v[176:177], v[192:193] neg_lo:[1,0,0] neg_hi:[1,0,0]
	v_pk_fma_f32 v[170:171], v[170:171], v[178:179], v[192:193] neg_lo:[1,0,0] neg_hi:[1,0,0]
	v_pk_fma_f32 v[172:173], v[172:173], v[180:181], v[192:193] neg_lo:[1,0,0] neg_hi:[1,0,0]
	v_pk_fma_f32 v[158:159], v[150:151], v[158:159], v[158:159]
	v_pk_fma_f32 v[160:161], v[152:153], v[160:161], v[160:161]
	v_pk_fma_f32 v[162:163], v[154:155], v[162:163], v[162:163]
	v_pk_fma_f32 v[164:165], v[156:157], v[164:165], v[164:165]
	v_pk_fma_f32 v[174:175], v[166:167], v[174:175], v[174:175]
	v_pk_fma_f32 v[176:177], v[168:169], v[176:177], v[176:177]
	v_pk_fma_f32 v[178:179], v[170:171], v[178:179], v[178:179]
	v_pk_fma_f32 v[180:181], v[172:173], v[180:181], v[180:181]
	v_cvt_pk_bf16_f32 v150, v162, v163
	v_cvt_pk_bf16_f32 v151, v164, v165
	v_cvt_pk_bf16_f32 v152, v158, v159
	v_cvt_pk_bf16_f32 v153, v160, v161
	v_cvt_pk_bf16_f32 v166, v178, v179
	v_cvt_pk_bf16_f32 v167, v180, v181
	v_cvt_pk_bf16_f32 v168, v174, v175
	v_cvt_pk_bf16_f32 v169, v176, v177
	global_store_dwordx4 v[182:183], v[150:153], off offset:256
	global_store_dwordx4 v[184:185], v[166:169], off offset:256
	v_pk_add_f32 v[30:31], v[30:31], v[142:143]
	v_pk_add_f32 v[32:33], v[32:33], v[144:145]
	v_pk_add_f32 v[26:27], v[26:27], v[146:147]
	v_pk_add_f32 v[28:29], v[28:29], v[148:149]
	v_pk_add_f32 v[22:23], v[22:23], v[142:143]
	v_pk_add_f32 v[24:25], v[24:25], v[144:145]
	v_pk_add_f32 v[18:19], v[18:19], v[146:147]
	v_pk_add_f32 v[20:21], v[20:21], v[148:149]
	v_min_f32_e64 v150, -v26, s79
	v_min_f32_e64 v151, -v27, s79
	v_min_f32_e64 v152, -v28, s79
	v_min_f32_e64 v153, -v29, s79
	v_min_f32_e64 v154, -v30, s79
	v_min_f32_e64 v155, -v31, s79
	v_min_f32_e64 v156, -v32, s79
	v_min_f32_e64 v157, -v33, s79
	v_min_f32_e64 v166, -v18, s79
	v_min_f32_e64 v167, -v19, s79
	v_min_f32_e64 v168, -v20, s79
	v_min_f32_e64 v169, -v21, s79
	v_min_f32_e64 v170, -v22, s79
	v_min_f32_e64 v171, -v23, s79
	v_min_f32_e64 v172, -v24, s79
	v_min_f32_e64 v173, -v25, s79
	v_pk_mul_f32 v[150:151], v[150:151], v[190:191]
	v_pk_mul_f32 v[152:153], v[152:153], v[190:191]
	v_pk_mul_f32 v[154:155], v[154:155], v[190:191]
	v_pk_mul_f32 v[156:157], v[156:157], v[190:191]
	v_pk_mul_f32 v[166:167], v[166:167], v[190:191]
	v_pk_mul_f32 v[168:169], v[168:169], v[190:191]
	v_pk_mul_f32 v[170:171], v[170:171], v[190:191]
	v_pk_mul_f32 v[172:173], v[172:173], v[190:191]
	v_exp_f32_e32 v150, v150
	v_exp_f32_e32 v151, v151
	v_exp_f32_e32 v152, v152
	v_exp_f32_e32 v153, v153
	v_exp_f32_e32 v154, v154
	v_exp_f32_e32 v155, v155
	v_exp_f32_e32 v156, v156
	v_exp_f32_e32 v157, v157
	v_exp_f32_e32 v166, v166
	v_exp_f32_e32 v167, v167
	v_exp_f32_e32 v168, v168
	v_exp_f32_e32 v169, v169
	v_exp_f32_e32 v170, v170
	v_exp_f32_e32 v171, v171
	v_exp_f32_e32 v172, v172
	v_exp_f32_e32 v173, v173
	v_add_co_u32_e32 v182, vcc, s75, v200
	s_nop 1
	v_addc_co_u32_e32 v183, vcc, 0, v201, vcc
	v_add_co_u32_e32 v184, vcc, s76, v200
	s_nop 1
	v_addc_co_u32_e32 v185, vcc, 0, v201, vcc
	v_pk_add_f32 v[150:151], v[150:151], v[192:193]
	v_pk_add_f32 v[152:153], v[152:153], v[192:193]
	v_pk_add_f32 v[154:155], v[154:155], v[192:193]
	v_pk_add_f32 v[156:157], v[156:157], v[192:193]
	v_pk_add_f32 v[166:167], v[166:167], v[192:193]
	v_pk_add_f32 v[168:169], v[168:169], v[192:193]
	v_pk_add_f32 v[170:171], v[170:171], v[192:193]
	v_pk_add_f32 v[172:173], v[172:173], v[192:193]
	v_rcp_f32_e32 v158, v150
	v_rcp_f32_e32 v159, v151
	v_rcp_f32_e32 v160, v152
	v_rcp_f32_e32 v161, v153
	v_rcp_f32_e32 v162, v154
	v_rcp_f32_e32 v163, v155
	v_rcp_f32_e32 v164, v156
	v_rcp_f32_e32 v165, v157
	v_rcp_f32_e32 v174, v166
	v_rcp_f32_e32 v175, v167
	v_rcp_f32_e32 v176, v168
	v_rcp_f32_e32 v177, v169
	v_rcp_f32_e32 v178, v170
	v_rcp_f32_e32 v179, v171
	v_rcp_f32_e32 v180, v172
	v_rcp_f32_e32 v181, v173
	s_nop 0
	v_pk_fma_f32 v[150:151], v[150:151], v[158:159], v[192:193] neg_lo:[1,0,0] neg_hi:[1,0,0]
	v_pk_fma_f32 v[152:153], v[152:153], v[160:161], v[192:193] neg_lo:[1,0,0] neg_hi:[1,0,0]
	v_pk_fma_f32 v[154:155], v[154:155], v[162:163], v[192:193] neg_lo:[1,0,0] neg_hi:[1,0,0]
	v_pk_fma_f32 v[156:157], v[156:157], v[164:165], v[192:193] neg_lo:[1,0,0] neg_hi:[1,0,0]
	v_pk_fma_f32 v[166:167], v[166:167], v[174:175], v[192:193] neg_lo:[1,0,0] neg_hi:[1,0,0]
	v_pk_fma_f32 v[168:169], v[168:169], v[176:177], v[192:193] neg_lo:[1,0,0] neg_hi:[1,0,0]
	v_pk_fma_f32 v[170:171], v[170:171], v[178:179], v[192:193] neg_lo:[1,0,0] neg_hi:[1,0,0]
	v_pk_fma_f32 v[172:173], v[172:173], v[180:181], v[192:193] neg_lo:[1,0,0] neg_hi:[1,0,0]
	v_pk_fma_f32 v[158:159], v[150:151], v[158:159], v[158:159]
	v_pk_fma_f32 v[160:161], v[152:153], v[160:161], v[160:161]
	v_pk_fma_f32 v[162:163], v[154:155], v[162:163], v[162:163]
	v_pk_fma_f32 v[164:165], v[156:157], v[164:165], v[164:165]
	v_pk_fma_f32 v[174:175], v[166:167], v[174:175], v[174:175]
	v_pk_fma_f32 v[176:177], v[168:169], v[176:177], v[176:177]
	v_pk_fma_f32 v[178:179], v[170:171], v[178:179], v[178:179]
	v_pk_fma_f32 v[180:181], v[172:173], v[180:181], v[180:181]
	v_cvt_pk_bf16_f32 v150, v162, v163
	v_cvt_pk_bf16_f32 v151, v164, v165
	v_cvt_pk_bf16_f32 v152, v158, v159
	v_cvt_pk_bf16_f32 v153, v160, v161
	v_cvt_pk_bf16_f32 v166, v178, v179
	v_cvt_pk_bf16_f32 v167, v180, v181
	v_cvt_pk_bf16_f32 v168, v174, v175
	v_cvt_pk_bf16_f32 v169, v176, v177
	global_store_dwordx4 v[182:183], v[150:153], off offset:256
	global_store_dwordx4 v[184:185], v[166:169], off offset:256
	v_pk_add_f32 v[14:15], v[14:15], v[142:143]
	v_pk_add_f32 v[16:17], v[16:17], v[144:145]
	v_pk_add_f32 v[10:11], v[10:11], v[146:147]
	v_pk_add_f32 v[12:13], v[12:13], v[148:149]
	v_pk_add_f32 v[6:7], v[6:7], v[142:143]
	v_pk_add_f32 v[8:9], v[8:9], v[144:145]
	v_pk_add_f32 v[2:3], v[2:3], v[146:147]
	v_pk_add_f32 v[4:5], v[4:5], v[148:149]
	v_min_f32_e64 v150, -v10, s79
	v_min_f32_e64 v151, -v11, s79
	v_min_f32_e64 v152, -v12, s79
	v_min_f32_e64 v153, -v13, s79
	v_min_f32_e64 v154, -v14, s79
	v_min_f32_e64 v155, -v15, s79
	v_min_f32_e64 v156, -v16, s79
	v_min_f32_e64 v157, -v17, s79
	v_min_f32_e64 v166, -v2, s79
	v_min_f32_e64 v167, -v3, s79
	v_min_f32_e64 v168, -v4, s79
	v_min_f32_e64 v169, -v5, s79
	v_min_f32_e64 v170, -v6, s79
	v_min_f32_e64 v171, -v7, s79
	v_min_f32_e64 v172, -v8, s79
	v_min_f32_e64 v173, -v9, s79
	v_pk_mul_f32 v[150:151], v[150:151], v[190:191]
	v_pk_mul_f32 v[152:153], v[152:153], v[190:191]
	v_pk_mul_f32 v[154:155], v[154:155], v[190:191]
	v_pk_mul_f32 v[156:157], v[156:157], v[190:191]
	v_pk_mul_f32 v[166:167], v[166:167], v[190:191]
	v_pk_mul_f32 v[168:169], v[168:169], v[190:191]
	v_pk_mul_f32 v[170:171], v[170:171], v[190:191]
	v_pk_mul_f32 v[172:173], v[172:173], v[190:191]
	v_exp_f32_e32 v150, v150
	v_exp_f32_e32 v151, v151
	v_exp_f32_e32 v152, v152
	v_exp_f32_e32 v153, v153
	v_exp_f32_e32 v154, v154
	v_exp_f32_e32 v155, v155
	v_exp_f32_e32 v156, v156
	v_exp_f32_e32 v157, v157
	v_exp_f32_e32 v166, v166
	v_exp_f32_e32 v167, v167
	v_exp_f32_e32 v168, v168
	v_exp_f32_e32 v169, v169
	v_exp_f32_e32 v170, v170
	v_exp_f32_e32 v171, v171
	v_exp_f32_e32 v172, v172
	v_exp_f32_e32 v173, v173
	v_add_co_u32_e32 v182, vcc, s77, v200
	s_nop 1
	v_addc_co_u32_e32 v183, vcc, 0, v201, vcc
	v_add_co_u32_e32 v184, vcc, s78, v200
	s_nop 1
	v_addc_co_u32_e32 v185, vcc, 0, v201, vcc
	v_pk_add_f32 v[150:151], v[150:151], v[192:193]
	v_pk_add_f32 v[152:153], v[152:153], v[192:193]
	v_pk_add_f32 v[154:155], v[154:155], v[192:193]
	v_pk_add_f32 v[156:157], v[156:157], v[192:193]
	v_pk_add_f32 v[166:167], v[166:167], v[192:193]
	v_pk_add_f32 v[168:169], v[168:169], v[192:193]
	v_pk_add_f32 v[170:171], v[170:171], v[192:193]
	v_pk_add_f32 v[172:173], v[172:173], v[192:193]
	v_rcp_f32_e32 v158, v150
	v_rcp_f32_e32 v159, v151
	v_rcp_f32_e32 v160, v152
	v_rcp_f32_e32 v161, v153
	v_rcp_f32_e32 v162, v154
	v_rcp_f32_e32 v163, v155
	v_rcp_f32_e32 v164, v156
	v_rcp_f32_e32 v165, v157
	v_rcp_f32_e32 v174, v166
	v_rcp_f32_e32 v175, v167
	v_rcp_f32_e32 v176, v168
	v_rcp_f32_e32 v177, v169
	v_rcp_f32_e32 v178, v170
	v_rcp_f32_e32 v179, v171
	v_rcp_f32_e32 v180, v172
	v_rcp_f32_e32 v181, v173
	s_nop 0
	v_pk_fma_f32 v[150:151], v[150:151], v[158:159], v[192:193] neg_lo:[1,0,0] neg_hi:[1,0,0]
	v_pk_fma_f32 v[152:153], v[152:153], v[160:161], v[192:193] neg_lo:[1,0,0] neg_hi:[1,0,0]
	v_pk_fma_f32 v[154:155], v[154:155], v[162:163], v[192:193] neg_lo:[1,0,0] neg_hi:[1,0,0]
	v_pk_fma_f32 v[156:157], v[156:157], v[164:165], v[192:193] neg_lo:[1,0,0] neg_hi:[1,0,0]
	v_pk_fma_f32 v[166:167], v[166:167], v[174:175], v[192:193] neg_lo:[1,0,0] neg_hi:[1,0,0]
	v_pk_fma_f32 v[168:169], v[168:169], v[176:177], v[192:193] neg_lo:[1,0,0] neg_hi:[1,0,0]
	v_pk_fma_f32 v[170:171], v[170:171], v[178:179], v[192:193] neg_lo:[1,0,0] neg_hi:[1,0,0]
	v_pk_fma_f32 v[172:173], v[172:173], v[180:181], v[192:193] neg_lo:[1,0,0] neg_hi:[1,0,0]
	v_pk_fma_f32 v[158:159], v[150:151], v[158:159], v[158:159]
	v_pk_fma_f32 v[160:161], v[152:153], v[160:161], v[160:161]
	v_pk_fma_f32 v[162:163], v[154:155], v[162:163], v[162:163]
	v_pk_fma_f32 v[164:165], v[156:157], v[164:165], v[164:165]
	v_pk_fma_f32 v[174:175], v[166:167], v[174:175], v[174:175]
	v_pk_fma_f32 v[176:177], v[168:169], v[176:177], v[176:177]
	v_pk_fma_f32 v[178:179], v[170:171], v[178:179], v[178:179]
	v_pk_fma_f32 v[180:181], v[172:173], v[180:181], v[180:181]
	v_cvt_pk_bf16_f32 v150, v162, v163
	v_cvt_pk_bf16_f32 v151, v164, v165
	v_cvt_pk_bf16_f32 v152, v158, v159
	v_cvt_pk_bf16_f32 v153, v160, v161
	v_cvt_pk_bf16_f32 v166, v178, v179
	v_cvt_pk_bf16_f32 v167, v180, v181
	v_cvt_pk_bf16_f32 v168, v174, v175
	v_cvt_pk_bf16_f32 v169, v176, v177
	global_store_dwordx4 v[182:183], v[150:153], off offset:256
	global_store_dwordx4 v[184:185], v[166:169], off offset:256
	s_andn2_b64 vcc, exec, s[52:53]
	s_mov_b64 s[8:9], -1
	s_cbranch_vccnz .LBB0_1698
